# P4 de-phasing of the two-unit workgroups (>= 32) in four sub-groups by (block>>3)&3: start delays 0 / 3.4 / 6.8 / 10.2 us (was two sub-groups 0 / 6.8 us)
# baseline (speedup 1.0000x reference)
.LBB0_2106:
	s_or_b64 exec, exec, s[0:1]
	s_cmpk_gt_i32 s96, 0x21f
	s_waitcnt lgkmcnt(0)
	s_barrier
	s_cbranch_scc1 .LBB0_2180
	s_cmp_lt_u32 s96, 32
	s_cbranch_scc1 .Lstg4_done
	s_bfe_u32 s4, s96, 0x20003
	s_cmp_eq_u32 s4, 0
	s_cbranch_scc1 .Lstg4_done
.Lstg4_loop:
	s_sleep 127
	s_sub_i32 s4, s4, 1
	s_cmp_lg_u32 s4, 0
	s_cbranch_scc1 .Lstg4_loop
